# attention loop: K-fragment prefetch across the vote barrier + QK^T MFMAs first, exp interleaved with PV MFMAs, 2-deep KV register prefetch; first grid sync = lean counter barrier
# speedup vs baseline: 1.0121x; 1.0121x over previous
.LBB0_42:
	v_lshrrev_b32_e32 v2, 20, v0
	v_lshrrev_b32_e32 v0, 10, v0
	v_or_b32_e32 v0, v0, v2
	s_movk_i32 s0, 0x3ff
	v_and_or_b32 v0, v0, s0, v1
	v_cmp_eq_u32_e32 vcc, 0, v0
	s_waitcnt vmcnt(0) lgkmcnt(0)
	s_barrier
	s_and_saveexec_b64 s[0:1], vcc
	s_cbranch_execz .LBB0_52
	buffer_wbl2 sc1
	s_waitcnt vmcnt(0)
	v_mov_b32_e32 v0, 0
	v_mov_b32_e32 v1, 1
	global_atomic_add v0, v1, s[92:93] offset:128
	global_load_dword v1, v0, s[92:93] offset:128 sc1
	s_waitcnt vmcnt(0)
	v_cmp_le_u32_e32 vcc, s33, v1
	s_cbranch_vccnz .Lgb0_done
.Lgb0_poll:
	s_sleep 1
	global_load_dword v1, v0, s[92:93] offset:128 sc1
	s_waitcnt vmcnt(0)
	v_cmp_gt_u32_e32 vcc, s33, v1
	s_cbranch_vccnz .Lgb0_poll
.Lgb0_done:
	buffer_inv sc1
	s_waitcnt vmcnt(0)
.LBB0_52:
	s_or_b64 exec, exec, s[0:1]
	s_cmpk_lt_i32 s2, 0x800
	s_cselect_b64 s[0:1], -1, 0
	s_cmpk_gt_i32 s2, 0x7ff
	s_barrier
	v_mbcnt_lo_u32_b32 v8, -1, 0
	v_mbcnt_hi_u32_b32 v8, -1, v8
	s_cbranch_scc1 .LBB0_58
	s_ashr_i32 s3, s2, 31
	s_lshr_b32 s3, s3, 29
	s_add_i32 s3, s2, s3
	s_and_b32 s4, s3, -8
	s_sub_i32 s6, s2, s4
	s_cmp_gt_i32 s6, -1
	s_cbranch_scc0 .LBB0_55
	s_lshl_b32 s7, s6, 8
	s_cbranch_execz .LBB0_56
	s_branch .LBB0_57

.LBB0_240:
	s_waitcnt vmcnt(11)
	ds_write_b128 v146, v[12:15]
	v_add_u32_e32 v12, v187, v190
	s_waitcnt vmcnt(10)
	ds_write_b128 v12, v[0:3] offset:52224
	s_waitcnt vmcnt(9)
	ds_write_b128 v146, v[4:7] offset:17408
	s_waitcnt vmcnt(8)
	ds_write_b128 v197, v[8:11]
	s_waitcnt vmcnt(5)
	ds_write_b128 v146, v[16:19] offset:8704
	s_waitcnt vmcnt(4)
	ds_write_b128 v12, v[20:23] offset:62464
	s_waitcnt vmcnt(3)
	ds_write_b128 v146, v[24:27] offset:26112
	s_waitcnt vmcnt(2)
	ds_write_b128 v197, v[28:31] offset:10240
	s_lshl_b32 s14, s39, 6
	s_sub_i32 s14, s14, 0x80
	s_max_i32 s14, s14, 0
	s_mov_b32 s15, 0
	s_lshl_b64 s[14:15], s[14:15], 9
	v_lshl_add_u64 v[166:167], v[158:159], 0, s[14:15]
	s_add_u32 s14, s14, 0x4000
	s_addc_u32 s15, s15, 0
	global_load_dwordx4 v[214:217], v[166:167], off
	global_load_dwordx4 v[218:221], v[166:167], off offset:256
	v_lshl_add_u64 v[166:167], v[158:159], 0, s[14:15]
	global_load_dwordx4 v[222:225], v[166:167], off
	global_load_dwordx4 v[226:229], v[166:167], off offset:256
	s_mov_b32 s32, 0
	s_and_saveexec_b64 s[20:21], s[8:9]
	ds_write_b32 v188, v97 offset:48
	s_or_b64 exec, exec, s[20:21]
	s_lshl_b32 s5, s0, 7
	s_andn2_b64 vcc, exec, s[50:51]
	s_waitcnt lgkmcnt(0)
	s_barrier
	s_cbranch_vccnz .LBB0_244
	s_barrier
.LBB0_244:
	v_add_f32_e32 v0, v33, v34
	v_mul_f32_e32 v1, 0x4f800000, v0
	v_cmp_gt_f32_e32 vcc, s80, v0
	s_add_i32 s0, s0, 1
	v_mov_b32_e32 v14, v97
	v_cndmask_b32_e32 v0, v0, v1, vcc
	v_sqrt_f32_e32 v1, v0
	v_mov_b32_e32 v15, v97
	v_mov_b32_e32 v4, v97
	v_mov_b32_e32 v5, v97
	v_add_u32_e32 v2, -1, v1
	v_fma_f32 v3, -v2, v1, v0
	v_cmp_ge_f32_e64 s[20:21], 0, v3
	v_add_u32_e32 v3, 1, v1
	v_mov_b32_e32 v6, v97
	v_cndmask_b32_e64 v2, v1, v2, s[20:21]
	v_fma_f32 v1, -v3, v1, v0
	v_cmp_lt_f32_e64 s[20:21], 0, v1
	v_mov_b32_e32 v7, v97
	v_mov_b32_e32 v8, v97
	v_cndmask_b32_e64 v1, v2, v3, s[20:21]
	v_mul_f32_e32 v2, 0x37800000, v1
	v_cndmask_b32_e32 v1, v1, v2, vcc
	v_cmp_class_f32_e32 vcc, v0, v195
	v_mov_b32_e32 v3, v97
	v_mov_b32_e32 v9, v97
	v_cndmask_b32_e32 v0, v1, v0, vcc
	v_cvt_f32_ubyte0_e32 v1, s0
	s_mov_b32 s0, 0x42fc0000
	v_cmp_lt_f32_e32 vcc, s0, v1
	s_and_b64 s[0:1], vcc, exec
	s_cselect_b32 s0, 0xffffffc0, 0
	v_cndmask_b32_e32 v2, 0, v199, vcc
	v_sub_f32_e32 v1, v2, v1
	v_exp_f32_e32 v1, v1
	v_mul_f32_e32 v160, 0x3f8020c5, v0
	s_lshl_b32 s12, s13, 3
	s_lshl_b32 s14, s13, 1
	v_ldexp_f32 v0, v1, s0
	v_mul_f32_e32 v161, 0x3fb8aa3b, v0
	v_cvt_pk_bf16_f32 v1, v161, 0
	v_lshlrev_b32_e32 v1, 16, v1
	s_mov_b32 s0, 0x3fb8aa3b
	v_fma_f32 v0, v0, s0, -v1
	v_cvt_pk_bf16_f32 v0, v1, v0
	v_cndmask_b32_e64 v96, 0, v0, s[10:11]
	v_add_f32_e32 v0, v161, v161
	v_readlane_b32 s0, v255, 24
	v_readfirstlane_b32 s68, v0
	s_lshl_b32 s13, s13, 7
	v_mov_b32_e32 v0, v97
	v_mov_b32_e32 v1, v97
	v_mov_b32_e32 v2, v97
	v_mov_b32_e32 v10, v97
	v_mov_b32_e32 v11, v97
	v_mov_b32_e32 v12, v97
	v_mov_b32_e32 v13, v97
	v_mov_b64_e32 v[30:31], v[14:15]
	v_mov_b64_e32 v[46:47], v[14:15]
	v_mov_b64_e32 v[62:63], v[14:15]
	s_mov_b32 s38, 0
	v_mov_b32_e32 v98, v97
	v_mov_b32_e32 v99, v97
	s_add_i32 s39, s39, s0
	s_mov_b32 s69, s68
	s_mov_b32 s70, s68
	s_mov_b32 s71, s68
	s_mov_b32 s81, s68
	s_mov_b32 s83, s68
	s_mov_b32 s84, s68
	s_mov_b32 s89, s68
	s_mov_b32 s90, s68
	s_mov_b32 s91, s68
	s_mov_b32 s92, s68
	s_mov_b32 s93, s68
	s_mov_b32 s94, s68
	s_mov_b32 s95, s68
	s_mov_b32 s96, s68
	s_mov_b32 s97, s68
	s_mov_b32 s98, s68
	s_mov_b32 s99, s68
	s_mov_b32 s0, s68
	s_mov_b32 s1, s68
	s_mov_b32 s73, s68
	s_mov_b32 s74, s68
	s_mov_b32 s85, s68
	s_mov_b32 s87, s68
	s_mov_b32 s86, s68
	s_mov_b32 s36, s68
	s_mov_b32 s37, s68
	s_mov_b32 s44, s68
	s_mov_b32 s45, s68
	s_mov_b32 s46, s68
	s_mov_b32 s47, s68
	s_mov_b32 s88, s68
	s_sub_i32 s12, 0x1bdf8, s12
	s_add_i32 s75, s14, 0xffffff81
	s_add_i32 s64, s14, 0xffffff80
	s_sub_i32 s65, 0, s13
	s_sub_i32 s13, 0, s14
	v_mov_b32_e32 v162, 0xf149f2ca
	v_mov_b32_e32 v153, 0
	s_mov_b32 s14, 2
	v_mov_b32_e32 v164, 0
	s_mov_b32 s15, 0
	v_mov_b32_e32 v155, v149
	v_mov_b64_e32 v[28:29], v[12:13]
	v_mov_b64_e32 v[26:27], v[10:11]
	v_mov_b64_e32 v[24:25], v[8:9]
	v_mov_b64_e32 v[22:23], v[6:7]
	v_mov_b64_e32 v[20:21], v[4:5]
	v_mov_b64_e32 v[18:19], v[2:3]
	v_mov_b64_e32 v[16:17], v[0:1]
	v_mov_b64_e32 v[44:45], v[12:13]
	v_mov_b64_e32 v[42:43], v[10:11]
	v_mov_b64_e32 v[40:41], v[8:9]
	v_mov_b64_e32 v[38:39], v[6:7]
	v_mov_b64_e32 v[36:37], v[4:5]
	v_mov_b64_e32 v[34:35], v[2:3]
	v_mov_b64_e32 v[32:33], v[0:1]
	v_mov_b64_e32 v[60:61], v[12:13]
	v_mov_b64_e32 v[58:59], v[10:11]
	v_mov_b64_e32 v[56:57], v[8:9]
	v_mov_b64_e32 v[54:55], v[6:7]
	v_mov_b64_e32 v[52:53], v[4:5]
	v_mov_b64_e32 v[50:51], v[2:3]
	v_mov_b64_e32 v[48:49], v[0:1]
	s_mov_b32 s16, 0
	s_add_i32 s17, s78, s12
	v_mov_b32_e32 v211, s17
	ds_read_b32 v210, v211
	v_mov_b32_e32 v178, v193
	ds_read_b128 v[230:233], v178
	ds_read_b128 v[234:237], v178 offset:32
	ds_read_b128 v[238:241], v178 offset:64
	ds_read_b128 v[242:245], v178 offset:96
	ds_read_b128 v[246:249], v178 offset:8704
	ds_read_b128 v[250:253], v178 offset:8736
	ds_read_b128 v[200:203], v178 offset:8768
	ds_read_b128 v[204:207], v178 offset:8800
	v_mfma_f32_32x32x16_bf16 v[80:95], v[100:103], v[96:99], 0
	v_mfma_f32_32x32x16_bf16 v[64:79], v[104:107], v[96:99], 0
	s_waitcnt lgkmcnt(7)
	v_mfma_f32_32x32x16_bf16 v[80:95], v[230:233], v[108:111], v[80:95]
	s_waitcnt lgkmcnt(6)
	v_mfma_f32_32x32x16_bf16 v[80:95], v[234:237], v[112:115], v[80:95]
	s_waitcnt lgkmcnt(5)
	v_mfma_f32_32x32x16_bf16 v[80:95], v[238:241], v[116:119], v[80:95]
	s_waitcnt lgkmcnt(4)
	v_mfma_f32_32x32x16_bf16 v[80:95], v[242:245], v[120:123], v[80:95]
	s_waitcnt lgkmcnt(3)
	v_mfma_f32_32x32x16_bf16 v[64:79], v[246:249], v[108:111], v[64:79]
	s_waitcnt lgkmcnt(2)
	v_mfma_f32_32x32x16_bf16 v[64:79], v[250:253], v[112:115], v[64:79]
	s_waitcnt lgkmcnt(1)
	v_mfma_f32_32x32x16_bf16 v[64:79], v[200:203], v[116:119], v[64:79]
	s_waitcnt lgkmcnt(0)
	v_mfma_f32_32x32x16_bf16 v[64:79], v[204:207], v[120:123], v[64:79]
.LBB0_245:
	s_add_i32 s17, s13, s38
	s_addk_i32 s17, 0x7f
	s_cmp_le_i32 s17, s39
	s_cselect_b64 s[20:21], -1, 0
	v_cmp_eq_u32_e32 vcc, 0, v164
	s_and_b64 vcc, s[20:21], vcc
	s_nop 0
	v_cndmask_b32_e64 v176, 0, 1, vcc
	v_cmp_ne_u32_e64 s[20:21], 1, v176
	s_andn2_b64 vcc, exec, vcc
	s_cbranch_vccnz .LBB0_253
	s_cmp_lg_u32 s79, s38
	s_cbranch_scc1 .LBB0_248
	v_add_u32_e32 v163, s15, v194
	v_add_u32_e32 v164, 64, v163
	v_add_u32_e32 v165, 0x41, v163
	v_add_u32_e32 v166, 0x42, v163
	v_add_u32_e32 v167, 0x43, v163
	v_add_u32_e32 v168, 0x44, v163
	v_add_u32_e32 v169, 0x45, v163
	v_add_u32_e32 v170, 0x46, v163
	v_add_u32_e32 v171, 0x47, v163
	v_add_u32_e32 v172, 0x50, v163
	v_add_u32_e32 v173, 0x51, v163
	v_add_u32_e32 v174, 0x52, v163
	v_add_u32_e32 v175, 0x53, v163
	v_add_u32_e32 v176, 0x54, v163
	v_add_u32_e32 v177, 0x55, v163
	v_add_u32_e32 v178, 0x56, v163
	v_add_u32_e32 v179, 0x57, v163
	v_add_u32_e32 v180, 0x60, v163
	v_add_u32_e32 v181, 0x61, v163
	v_add_u32_e32 v182, 0x62, v163
	v_add_u32_e32 v183, 0x63, v163
	v_add_u32_e32 v184, 0x64, v163
	v_add_u32_e32 v185, 0x65, v163
	v_add_u32_e32 v200, 0x66, v163
	v_add_u32_e32 v201, 0x67, v163
	v_add_u32_e32 v202, 0x70, v163
	v_add_u32_e32 v203, 0x71, v163
	v_add_u32_e32 v204, 0x72, v163
	v_add_u32_e32 v205, 0x73, v163
	v_add_u32_e32 v206, 0x74, v163
	v_add_u32_e32 v207, 0x75, v163
	v_add_u32_e32 v208, 0x76, v163
	v_add_u32_e32 v163, 0x77, v163
	v_cvt_f32_i32_e32 v208, v208
	v_cvt_f32_i32_e32 v163, v163
	v_cvt_f32_i32_e32 v206, v206
	v_cvt_f32_i32_e32 v207, v207
	v_cvt_f32_i32_e32 v204, v204
	v_cvt_f32_i32_e32 v205, v205
	v_cvt_f32_i32_e32 v202, v202
	v_cvt_f32_i32_e32 v203, v203
	v_cvt_f32_i32_e32 v200, v200
	v_cvt_f32_i32_e32 v201, v201
	v_max_f32_e32 v208, 0, v208
	v_max_f32_e32 v209, 0, v163
	s_xor_b32 s19, s88, 0x80000000
	s_xor_b32 s18, s47, 0x80000000
	v_cvt_f32_i32_e32 v184, v184
	v_cvt_f32_i32_e32 v185, v185
	v_max_f32_e32 v206, 0, v206
	v_max_f32_e32 v207, 0, v207
	v_pk_fma_f32 v[78:79], s[18:19], v[208:209], v[78:79]
	s_xor_b32 s19, s46, 0x80000000
	s_xor_b32 s18, s45, 0x80000000
	v_cvt_f32_i32_e32 v182, v182
	v_cvt_f32_i32_e32 v183, v183
	v_max_f32_e32 v204, 0, v204
	v_max_f32_e32 v205, 0, v205
	v_pk_fma_f32 v[76:77], s[18:19], v[206:207], v[76:77]
	s_xor_b32 s19, s44, 0x80000000
	s_xor_b32 s18, s37, 0x80000000
	v_cvt_f32_i32_e32 v180, v180
	v_cvt_f32_i32_e32 v181, v181
	v_max_f32_e32 v202, 0, v202
	v_max_f32_e32 v203, 0, v203
	v_pk_fma_f32 v[74:75], s[18:19], v[204:205], v[74:75]
	s_xor_b32 s19, s36, 0x80000000
	s_xor_b32 s18, s86, 0x80000000
	v_cvt_f32_i32_e32 v178, v178
	v_cvt_f32_i32_e32 v179, v179
	v_max_f32_e32 v200, 0, v200
	v_max_f32_e32 v201, 0, v201
	v_pk_fma_f32 v[72:73], s[18:19], v[202:203], v[72:73]
	s_xor_b32 s19, s87, 0x80000000
	s_xor_b32 s18, s85, 0x80000000
	v_cvt_f32_i32_e32 v176, v176
	v_cvt_f32_i32_e32 v177, v177
	v_max_f32_e32 v184, 0, v184
	v_max_f32_e32 v185, 0, v185
	v_pk_fma_f32 v[70:71], s[18:19], v[200:201], v[70:71]
	s_xor_b32 s19, s74, 0x80000000
	s_xor_b32 s18, s73, 0x80000000
	v_cvt_f32_i32_e32 v174, v174
	v_cvt_f32_i32_e32 v175, v175
	v_max_f32_e32 v182, 0, v182
	v_max_f32_e32 v183, 0, v183
	v_pk_fma_f32 v[68:69], s[18:19], v[184:185], v[68:69]
	s_xor_b32 s19, s1, 0x80000000
	s_xor_b32 s18, s0, 0x80000000
	v_cvt_f32_i32_e32 v172, v172
	v_cvt_f32_i32_e32 v173, v173
	v_max_f32_e32 v180, 0, v180
	v_max_f32_e32 v181, 0, v181
	v_pk_fma_f32 v[66:67], s[18:19], v[182:183], v[66:67]
	s_xor_b32 s19, s99, 0x80000000
	s_xor_b32 s18, s98, 0x80000000
	v_cvt_f32_i32_e32 v170, v170
	v_cvt_f32_i32_e32 v171, v171
	v_max_f32_e32 v178, 0, v178
	v_max_f32_e32 v179, 0, v179
	v_pk_fma_f32 v[64:65], s[18:19], v[180:181], v[64:65]
	s_xor_b32 s19, s97, 0x80000000
	s_xor_b32 s18, s96, 0x80000000
	v_cvt_f32_i32_e32 v168, v168
	v_cvt_f32_i32_e32 v169, v169
	v_max_f32_e32 v176, 0, v176
	v_max_f32_e32 v177, 0, v177
	v_pk_fma_f32 v[94:95], s[18:19], v[178:179], v[94:95]
	s_xor_b32 s19, s95, 0x80000000
	s_xor_b32 s18, s94, 0x80000000
	v_cvt_f32_i32_e32 v164, v164
	v_cvt_f32_i32_e32 v165, v165
	v_cvt_f32_i32_e32 v166, v166
	v_cvt_f32_i32_e32 v167, v167
	v_max_f32_e32 v174, 0, v174
	v_max_f32_e32 v175, 0, v175
	v_pk_fma_f32 v[92:93], s[18:19], v[176:177], v[92:93]
	s_xor_b32 s19, s93, 0x80000000
	s_xor_b32 s18, s92, 0x80000000
	v_max_f32_e32 v172, 0, v172
	v_max_f32_e32 v173, 0, v173
	v_pk_fma_f32 v[90:91], s[18:19], v[174:175], v[90:91]
	s_xor_b32 s19, s91, 0x80000000
	s_xor_b32 s18, s90, 0x80000000
	v_max_f32_e32 v170, 0, v170
	v_max_f32_e32 v171, 0, v171
	v_pk_fma_f32 v[88:89], s[18:19], v[172:173], v[88:89]
	s_xor_b32 s19, s89, 0x80000000
	s_xor_b32 s18, s84, 0x80000000
	v_max_f32_e32 v168, 0, v168
	v_max_f32_e32 v169, 0, v169
	v_pk_fma_f32 v[86:87], s[18:19], v[170:171], v[86:87]
	s_xor_b32 s19, s83, 0x80000000
	s_xor_b32 s18, s81, 0x80000000
	v_max_f32_e32 v164, 0, v164
	v_max_f32_e32 v165, 0, v165
	v_max_f32_e32 v166, 0, v166
	v_max_f32_e32 v167, 0, v167
	v_pk_fma_f32 v[84:85], s[18:19], v[168:169], v[84:85]
	s_xor_b32 s19, s71, 0x80000000
	s_xor_b32 s18, s70, 0x80000000
	v_pk_fma_f32 v[82:83], s[18:19], v[166:167], v[82:83]
	v_pk_fma_f32 v[80:81], s[68:69], v[164:165], v[80:81] neg_lo:[1,0,0] neg_hi:[1,0,0]
.LBB0_248:
	v_max3_f32 v166, v80, v81, v82
	v_max3_f32 v167, v88, v89, v90
	v_max3_f32 v166, v166, v83, v84
	v_max3_f32 v167, v167, v91, v92
	v_max3_f32 v166, v166, v85, v86
	v_max3_f32 v167, v167, v93, v94
	v_max3_f32 v166, v166, v87, v95
	v_cvt_f32_i32_e32 v165, v155
	v_max3_f32 v168, v64, v65, v66
	v_max3_f32 v169, v72, v73, v74
	v_max3_f32 v168, v168, v67, v68
	v_max3_f32 v169, v169, v75, v76
	v_max3_f32 v168, v168, v69, v70
	v_max3_f32 v169, v169, v77, v78
	v_max3_f32 v168, v168, v71, v79
	v_max3_f32 v166, v166, v167, v169
	v_max_f32_e32 v163, v166, v168
	v_fma_f32 v163, -v161, v165, v163
	v_mov_b32_e32 v166, v163
	s_nop 1
	v_permlane32_swap_b32_e32 v166, v163
	v_max3_f32 v163, v162, v163, v166
	v_cmp_gt_f32_e32 vcc, v163, v162
	s_cbranch_vccz .LBB0_250
	v_sub_f32_e32 v162, v162, v163
	v_exp_f32_e32 v162, v162
	s_nop 0
	v_mul_f32_e32 v153, v153, v162
	v_pk_mul_f32 v[62:63], v[62:63], v[162:163] op_sel_hi:[1,0]
	v_pk_mul_f32 v[60:61], v[60:61], v[162:163] op_sel_hi:[1,0]
	v_pk_mul_f32 v[58:59], v[58:59], v[162:163] op_sel_hi:[1,0]
	v_pk_mul_f32 v[56:57], v[56:57], v[162:163] op_sel_hi:[1,0]
	v_pk_mul_f32 v[54:55], v[54:55], v[162:163] op_sel_hi:[1,0]
	v_pk_mul_f32 v[52:53], v[52:53], v[162:163] op_sel_hi:[1,0]
	v_pk_mul_f32 v[50:51], v[50:51], v[162:163] op_sel_hi:[1,0]
	v_pk_mul_f32 v[48:49], v[48:49], v[162:163] op_sel_hi:[1,0]
	v_pk_mul_f32 v[46:47], v[46:47], v[162:163] op_sel_hi:[1,0]
	v_pk_mul_f32 v[44:45], v[44:45], v[162:163] op_sel_hi:[1,0]
	v_pk_mul_f32 v[42:43], v[42:43], v[162:163] op_sel_hi:[1,0]
	v_pk_mul_f32 v[40:41], v[40:41], v[162:163] op_sel_hi:[1,0]
	v_pk_mul_f32 v[38:39], v[38:39], v[162:163] op_sel_hi:[1,0]
	v_pk_mul_f32 v[36:37], v[36:37], v[162:163] op_sel_hi:[1,0]
	v_pk_mul_f32 v[34:35], v[34:35], v[162:163] op_sel_hi:[1,0]
	v_pk_mul_f32 v[32:33], v[32:33], v[162:163] op_sel_hi:[1,0]
	v_pk_mul_f32 v[30:31], v[30:31], v[162:163] op_sel_hi:[1,0]
	v_pk_mul_f32 v[28:29], v[28:29], v[162:163] op_sel_hi:[1,0]
	v_pk_mul_f32 v[26:27], v[26:27], v[162:163] op_sel_hi:[1,0]
	v_pk_mul_f32 v[24:25], v[24:25], v[162:163] op_sel_hi:[1,0]
	v_pk_mul_f32 v[22:23], v[22:23], v[162:163] op_sel_hi:[1,0]
	v_pk_mul_f32 v[20:21], v[20:21], v[162:163] op_sel_hi:[1,0]
	v_pk_mul_f32 v[18:19], v[18:19], v[162:163] op_sel_hi:[1,0]
	v_pk_mul_f32 v[16:17], v[16:17], v[162:163] op_sel_hi:[1,0]
	v_pk_mul_f32 v[14:15], v[14:15], v[162:163] op_sel_hi:[1,0]
	v_pk_mul_f32 v[12:13], v[12:13], v[162:163] op_sel_hi:[1,0]
	v_pk_mul_f32 v[10:11], v[10:11], v[162:163] op_sel_hi:[1,0]
	v_pk_mul_f32 v[8:9], v[8:9], v[162:163] op_sel_hi:[1,0]
	v_pk_mul_f32 v[6:7], v[6:7], v[162:163] op_sel_hi:[1,0]
	v_pk_mul_f32 v[4:5], v[4:5], v[162:163] op_sel_hi:[1,0]
	v_pk_mul_f32 v[2:3], v[2:3], v[162:163] op_sel_hi:[1,0]
	v_pk_mul_f32 v[0:1], v[0:1], v[162:163] op_sel_hi:[1,0]
.LBB0_250:
	s_cmp_eq_u32 s75, s38
	v_mov_b32_e32 v164, 0
	s_cbranch_scc1 .LBB0_252
	v_add_u32_e32 v162, 1, v155
	v_cvt_f32_i32_e32 v211, v162
	s_waitcnt lgkmcnt(0)
	v_pk_mul_f32 v[166:167], v[160:161], v[210:211]
	s_nop 0
	v_mov_b32_e32 v162, v166
	v_pk_add_f32 v[168:169], v[162:163], s[24:25]
	s_nop 0
	v_sub_f32_e32 v162, v168, v167
	v_cmp_lt_f32_e32 vcc, v162, v169
	s_cmp_eq_u64 vcc, exec
	s_cselect_b64 s[18:19], -1, 0
	v_cndmask_b32_e64 v164, 0, 1, s[18:19]
.LBB0_252:
	v_mul_f32_e32 v162, v161, v165
	v_add_f32_e32 v162, v162, v163
	v_sub_f32_e32 v80, v80, v162
	v_sub_f32_e32 v81, v81, v162
	v_sub_f32_e32 v82, v82, v162
	v_sub_f32_e32 v83, v83, v162
	v_sub_f32_e32 v84, v84, v162
	v_sub_f32_e32 v85, v85, v162
	v_sub_f32_e32 v86, v86, v162
	v_sub_f32_e32 v87, v87, v162
	v_exp_f32_e32 v80, v80
	v_exp_f32_e32 v81, v81
	v_exp_f32_e32 v82, v82
	v_exp_f32_e32 v83, v83
	v_exp_f32_e32 v84, v84
	v_exp_f32_e32 v85, v85
	v_exp_f32_e32 v86, v86
	v_exp_f32_e32 v87, v87
	v_add_f32_e32 v153, v153, v80
	v_add_f32_e32 v153, v153, v81
	v_add_f32_e32 v153, v153, v82
	v_add_f32_e32 v153, v153, v83
	v_add_f32_e32 v153, v153, v84
	v_add_f32_e32 v153, v153, v85
	v_add_f32_e32 v153, v153, v86
	v_add_f32_e32 v153, v153, v87
	v_cvt_pk_bf16_f32 v80, v80, v81
	v_cvt_pk_bf16_f32 v81, v82, v83
	v_cvt_pk_bf16_f32 v82, v84, v85
	v_cvt_pk_bf16_f32 v83, v86, v87
	s_branch .LBB0_254

.LBB0_254:
	s_and_b64 vcc, exec, s[20:21]
	s_barrier
	s_min_u32 s17, s4, 4
	s_lshl_b32 s17, s17, 6
	s_sub_i32 s17, s65, s17
	s_add_i32 s17, s15, s17
	s_mul_i32 s18, s14, 0x4400
	s_mul_i32 s19, s14, 0x5000
	s_add_i32 s40, s17, 0x1fc0
	v_add_u32_e32 v168, s18, v146
	v_add_u32_e32 v169, s19, v148
	s_lshl_b64 s[18:19], s[40:41], 9
	s_add_i32 s40, s17, 0x1fe0
	s_bitcmp1_b32 s32, 0
	s_cbranch_scc1 .Lattn_stage_r1
	s_waitcnt vmcnt(7)
	ds_write_b128 v168, v[128:131]
	s_waitcnt vmcnt(6)
	ds_write_b128 v169, v[124:127] offset:52224
	s_waitcnt vmcnt(5)
	ds_write_b128 v168, v[132:135] offset:8704
	s_waitcnt vmcnt(4)
	ds_write_b128 v169, v[136:139] offset:62464
	v_lshl_add_u64 v[170:171], v[158:159], 0, s[18:19]
	s_lshl_b64 s[18:19], s[40:41], 9
	global_load_dwordx4 v[128:131], v[170:171], off
	global_load_dwordx4 v[124:127], v[170:171], off offset:256
	v_lshl_add_u64 v[170:171], v[158:159], 0, s[18:19]
	global_load_dwordx4 v[132:135], v[170:171], off
	global_load_dwordx4 v[136:139], v[170:171], off offset:256
	s_branch .Lattn_stage_done
.Lattn_stage_r1:
	s_waitcnt vmcnt(7)
	ds_write_b128 v168, v[214:217]
	s_waitcnt vmcnt(6)
	ds_write_b128 v169, v[218:221] offset:52224
	s_waitcnt vmcnt(5)
	ds_write_b128 v168, v[222:225] offset:8704
	s_waitcnt vmcnt(4)
	ds_write_b128 v169, v[226:229] offset:62464
	v_lshl_add_u64 v[170:171], v[158:159], 0, s[18:19]
	s_lshl_b64 s[18:19], s[40:41], 9
	global_load_dwordx4 v[214:217], v[170:171], off
	global_load_dwordx4 v[218:221], v[170:171], off offset:256
	v_lshl_add_u64 v[170:171], v[158:159], 0, s[18:19]
	global_load_dwordx4 v[222:225], v[170:171], off
	global_load_dwordx4 v[226:229], v[170:171], off offset:256
.Lattn_stage_done:
	s_xor_b32 s32, s32, 1
	s_add_i32 s17, s12, 0xfffe4404
	s_and_b32 s17, s17, 4
	s_xor_b32 s40, s17, 4
	s_and_saveexec_b64 s[20:21], s[6:7]
	s_lshl_b32 s18, s40, 2
	s_add_i32 s18, s77, s18
	v_mov_b32_e32 v168, s18
	ds_write_b32 v168, v164
	s_or_b64 exec, exec, s[20:21]
	s_cbranch_vccnz .LBB0_256
	s_mul_i32 s17, s16, 0x5000
	v_add3_u32 v166, v192, s17, v189
	v_add_u32_e32 v167, 0xcc00, v166
	s_waitcnt lgkmcnt(2)
	ds_read_b64_tr_b16 v[230:231], v166 offset:52224
	ds_read_b64_tr_b16 v[232:233], v166 offset:53504
	ds_read_b64_tr_b16 v[234:235], v166 offset:52288
	ds_read_b64_tr_b16 v[236:237], v166 offset:53568
	ds_read_b64_tr_b16 v[238:239], v166 offset:52352
	ds_read_b64_tr_b16 v[240:241], v166 offset:53632
	ds_read_b64_tr_b16 v[242:243], v166 offset:52416
	ds_read_b64_tr_b16 v[244:245], v166 offset:53696
	ds_read_b64_tr_b16 v[246:247], v166 offset:57344
	ds_read_b64_tr_b16 v[248:249], v166 offset:58624
	ds_read_b64_tr_b16 v[250:251], v166 offset:57408
	ds_read_b64_tr_b16 v[252:253], v166 offset:58688
	v_sub_f32_e32 v88, v88, v162
	v_sub_f32_e32 v89, v89, v162
	v_sub_f32_e32 v90, v90, v162
	v_sub_f32_e32 v91, v91, v162
	v_sub_f32_e32 v92, v92, v162
	v_sub_f32_e32 v93, v93, v162
	v_sub_f32_e32 v94, v94, v162
	v_sub_f32_e32 v95, v95, v162
	s_waitcnt lgkmcnt(10)
	v_mfma_f32_32x32x16_bf16 v[48:63], v[230:233], v[80:83], v[48:63]
	v_exp_f32_e32 v88, v88
	v_exp_f32_e32 v89, v89
	v_exp_f32_e32 v90, v90
	v_exp_f32_e32 v91, v91
	v_exp_f32_e32 v92, v92
	v_exp_f32_e32 v93, v93
	v_exp_f32_e32 v94, v94
	ds_read_b64_tr_b16 v[230:231], v166 offset:57472
	ds_read_b64_tr_b16 v[232:233], v166 offset:58752
	s_waitcnt lgkmcnt(10)
	v_mfma_f32_32x32x16_bf16 v[32:47], v[234:237], v[80:83], v[32:47]
	v_exp_f32_e32 v95, v95
	v_add_f32_e32 v153, v153, v88
	v_add_f32_e32 v153, v153, v89
	v_add_f32_e32 v153, v153, v90
	v_add_f32_e32 v153, v153, v91
	v_add_f32_e32 v153, v153, v92
	ds_read_b64_tr_b16 v[234:235], v166 offset:57536
	ds_read_b64_tr_b16 v[236:237], v166 offset:58816
	s_waitcnt lgkmcnt(10)
	v_mfma_f32_32x32x16_bf16 v[16:31], v[238:241], v[80:83], v[16:31]
	v_add_f32_e32 v153, v153, v93
	v_add_f32_e32 v153, v153, v94
	v_add_f32_e32 v153, v153, v95
	v_cvt_pk_bf16_f32 v88, v88, v89
	v_cvt_pk_bf16_f32 v89, v90, v91
	v_cvt_pk_bf16_f32 v90, v92, v93
	ds_read_b64_tr_b16 v[238:239], v166 offset:62464
	ds_read_b64_tr_b16 v[240:241], v166 offset:63744
	s_waitcnt lgkmcnt(10)
	v_mfma_f32_32x32x16_bf16 v[0:15], v[242:245], v[80:83], v[0:15]
	v_cvt_pk_bf16_f32 v91, v94, v95
	v_sub_f32_e32 v64, v64, v162
	v_sub_f32_e32 v65, v65, v162
	v_sub_f32_e32 v66, v66, v162
	v_sub_f32_e32 v67, v67, v162
	v_sub_f32_e32 v68, v68, v162
	v_sub_f32_e32 v69, v69, v162
	ds_read_b64_tr_b16 v[242:243], v166 offset:62528
	ds_read_b64_tr_b16 v[244:245], v166 offset:63808
	s_waitcnt lgkmcnt(10)
	v_mfma_f32_32x32x16_bf16 v[48:63], v[246:249], v[88:91], v[48:63]
	v_sub_f32_e32 v70, v70, v162
	v_sub_f32_e32 v71, v71, v162
	v_exp_f32_e32 v64, v64
	v_exp_f32_e32 v65, v65
	v_exp_f32_e32 v66, v66
	v_exp_f32_e32 v67, v67
	ds_read_b64_tr_b16 v[246:247], v166 offset:62592
	ds_read_b64_tr_b16 v[248:249], v166 offset:63872
	s_waitcnt lgkmcnt(10)
	v_mfma_f32_32x32x16_bf16 v[32:47], v[250:253], v[88:91], v[32:47]
	v_exp_f32_e32 v68, v68
	v_exp_f32_e32 v69, v69
	v_exp_f32_e32 v70, v70
	v_exp_f32_e32 v71, v71
	v_add_f32_e32 v153, v153, v64
	v_add_f32_e32 v153, v153, v65
	ds_read_b64_tr_b16 v[250:251], v166 offset:62656
	ds_read_b64_tr_b16 v[252:253], v166 offset:63936
	s_waitcnt lgkmcnt(10)
	v_mfma_f32_32x32x16_bf16 v[16:31], v[230:233], v[88:91], v[16:31]
	v_add_f32_e32 v153, v153, v66
	v_add_f32_e32 v153, v153, v67
	v_add_f32_e32 v153, v153, v68
	v_add_f32_e32 v153, v153, v69
	v_add_f32_e32 v153, v153, v70
	v_add_f32_e32 v153, v153, v71
	v_cvt_pk_bf16_f32 v64, v64, v65
	ds_read_b64_tr_b16 v[230:231], v167 offset:15360
	ds_read_b64_tr_b16 v[232:233], v167 offset:16640
	s_waitcnt lgkmcnt(10)
	v_mfma_f32_32x32x16_bf16 v[0:15], v[234:237], v[88:91], v[0:15]
	v_cvt_pk_bf16_f32 v65, v66, v67
	v_cvt_pk_bf16_f32 v66, v68, v69
	v_cvt_pk_bf16_f32 v67, v70, v71
	v_sub_f32_e32 v72, v72, v162
	v_sub_f32_e32 v73, v73, v162
	v_sub_f32_e32 v74, v74, v162
	ds_read_b64_tr_b16 v[234:235], v167 offset:15424
	ds_read_b64_tr_b16 v[236:237], v167 offset:16704
	s_waitcnt lgkmcnt(10)
	v_mfma_f32_32x32x16_bf16 v[48:63], v[238:241], v[64:67], v[48:63]
	v_sub_f32_e32 v75, v75, v162
	v_sub_f32_e32 v76, v76, v162
	v_sub_f32_e32 v77, v77, v162
	v_sub_f32_e32 v78, v78, v162
	v_sub_f32_e32 v79, v79, v162
	v_exp_f32_e32 v72, v72
	ds_read_b64_tr_b16 v[238:239], v167 offset:15488
	ds_read_b64_tr_b16 v[240:241], v167 offset:16768
	s_waitcnt lgkmcnt(10)
	v_mfma_f32_32x32x16_bf16 v[32:47], v[242:245], v[64:67], v[32:47]
	v_exp_f32_e32 v73, v73
	v_exp_f32_e32 v74, v74
	v_exp_f32_e32 v75, v75
	v_exp_f32_e32 v76, v76
	v_exp_f32_e32 v77, v77
	v_exp_f32_e32 v78, v78
	v_exp_f32_e32 v79, v79
	ds_read_b64_tr_b16 v[242:243], v167 offset:15552
	ds_read_b64_tr_b16 v[244:245], v167 offset:16832
	s_waitcnt lgkmcnt(10)
	v_mfma_f32_32x32x16_bf16 v[16:31], v[246:249], v[64:67], v[16:31]
	v_add_f32_e32 v153, v153, v72
	v_add_f32_e32 v153, v153, v73
	v_add_f32_e32 v153, v153, v74
	v_add_f32_e32 v153, v153, v75
	v_add_f32_e32 v153, v153, v76
	v_add_f32_e32 v153, v153, v77
	s_waitcnt lgkmcnt(8)
	v_mfma_f32_32x32x16_bf16 v[0:15], v[250:253], v[64:67], v[0:15]
	v_add_f32_e32 v153, v153, v78
	v_add_f32_e32 v153, v153, v79
	v_cvt_pk_bf16_f32 v72, v72, v73
	v_cvt_pk_bf16_f32 v73, v74, v75
	v_cvt_pk_bf16_f32 v74, v76, v77
	v_cvt_pk_bf16_f32 v75, v78, v79
	s_nop 0
	s_waitcnt lgkmcnt(6)
	v_mfma_f32_32x32x16_bf16 v[48:63], v[230:233], v[72:75], v[48:63]
	s_waitcnt lgkmcnt(4)
	v_mfma_f32_32x32x16_bf16 v[32:47], v[234:237], v[72:75], v[32:47]
	s_waitcnt lgkmcnt(2)
	v_mfma_f32_32x32x16_bf16 v[16:31], v[238:241], v[72:75], v[16:31]
	s_waitcnt lgkmcnt(0)
	v_mfma_f32_32x32x16_bf16 v[0:15], v[242:245], v[72:75], v[0:15]
.LBB0_256:
	s_add_i32 s17, s78, s12
	s_add_i32 s17, s17, -4
	v_mov_b32_e32 v211, s17
	ds_read_b32 v210, v211
	s_add_i32 s17, s16, 1
	s_cmp_lg_u32 s16, 2
	s_cselect_b32 s17, s17, 0
	s_mul_i32 s17, s17, 0x4400
	v_add_u32_e32 v178, s17, v193
	ds_read_b128 v[230:233], v178
	ds_read_b128 v[234:237], v178 offset:32
	ds_read_b128 v[238:241], v178 offset:64
	ds_read_b128 v[242:245], v178 offset:96
	ds_read_b128 v[246:249], v178 offset:8704
	ds_read_b128 v[250:253], v178 offset:8736
	ds_read_b128 v[200:203], v178 offset:8768
	ds_read_b128 v[204:207], v178 offset:8800
	s_add_i32 s17, s12, 0xfffe4404
	s_and_b32 s17, s17, 4
	s_xor_b32 s40, s17, 4
	s_lshl_b32 s18, s40, 2
	s_add_i32 s18, s18, 0x1c040
	v_mov_b32_e32 v176, s18
	s_lshl_b32 s17, s17, 2
	s_add_i32 s17, s17, 0x1c060
	v_mov_b32_e32 v177, s17
	s_waitcnt lgkmcnt(9)
	s_barrier
	ds_read_b128 v[168:171], v176
	ds_read_b128 v[172:175], v177
	v_mfma_f32_32x32x16_bf16 v[80:95], v[100:103], v[96:99], 0
	v_mfma_f32_32x32x16_bf16 v[64:79], v[104:107], v[96:99], 0
	s_waitcnt lgkmcnt(9)
	v_mfma_f32_32x32x16_bf16 v[80:95], v[230:233], v[108:111], v[80:95]
	s_waitcnt lgkmcnt(8)
	v_mfma_f32_32x32x16_bf16 v[80:95], v[234:237], v[112:115], v[80:95]
	s_waitcnt lgkmcnt(7)
	v_mfma_f32_32x32x16_bf16 v[80:95], v[238:241], v[116:119], v[80:95]
	s_waitcnt lgkmcnt(6)
	v_mfma_f32_32x32x16_bf16 v[80:95], v[242:245], v[120:123], v[80:95]
	s_waitcnt lgkmcnt(5)
	v_mfma_f32_32x32x16_bf16 v[64:79], v[246:249], v[108:111], v[64:79]
	s_waitcnt lgkmcnt(4)
	v_mfma_f32_32x32x16_bf16 v[64:79], v[250:253], v[112:115], v[64:79]
	s_waitcnt lgkmcnt(3)
	v_mfma_f32_32x32x16_bf16 v[64:79], v[200:203], v[116:119], v[64:79]
	s_waitcnt lgkmcnt(2)
	v_mfma_f32_32x32x16_bf16 v[64:79], v[204:207], v[120:123], v[64:79]
	s_waitcnt lgkmcnt(0)
	v_and_b32_e32 v168, v168, v169
	v_and_b32_e32 v168, v168, v170
	v_and_b32_e32 v168, v168, v171
	v_and_b32_e32 v168, v168, v172
	v_and_b32_e32 v168, v168, v173
	v_and_b32_e32 v168, v168, v174
	v_and_b32_e32 v168, v168, v175
	v_cmp_ne_u32_e32 vcc, 0, v168
	s_cbranch_vccz .LBB0_260
	s_branch .LBB0_262
